# v039 + NA bias loads paired into ds_read2_b32 (24 fewer LDS instructions per iteration incl. prologue)
# speedup vs baseline: 1.0015x; 1.0015x over previous
; template <bool NA>
; __device__ __forceinline__ void attn_unit(LAS unsigned char* lds, const bf16_t* Q, const bf16_t* Kg, const bf16_t* Kr, const bf16_t* Vt, bf16_t* O,
;                                           int h, int seqrow0, int q0, int t0, int NT, int rows, int g0, const float* rpb_h, int wid) {
;     ...
;     A_QK(sA0, sA1, 0);
;     A_MASK(sA0, sA1, 0);
;     tmA = rowmax32(sA0, sA1);
.LBB0_733:
	v_lshlrev_b32_e32 v0, 4, v4
	v_mul_u32_u24_e32 v2, 0x90, v3
	v_add3_u32 v173, v0, v2, 0
	s_waitcnt vmcnt(0)
	s_waitcnt lgkmcnt(0)
	s_barrier
	ds_read_b128 v[6:9], v173
	ds_read_b128 v[10:13], v173 offset:32
	s_waitcnt vmcnt(3) lgkmcnt(1)
	v_mfma_f32_32x32x16_bf16 v[44:59], v[6:9], v[146:149], 0
	s_cmp_gt_i32 s81, -1
	s_cselect_b64 s[38:39], -1, 0
	s_add_i32 s10, s10, s84
	v_sub_co_u32_e64 v2, s[6:7], s10, 4
	s_nop 0
	v_readfirstlane_b32 s8, v2
	s_min_u32 s1, s8, s1
	s_waitcnt vmcnt(2) lgkmcnt(0)
	v_mfma_f32_32x32x16_bf16 v[44:59], v[10:13], v[150:153], v[44:59]
	ds_read_b128 v[6:9], v173 offset:4608
	ds_read_b128 v[10:13], v173 offset:4640
	s_and_b64 s[6:7], s[6:7], exec
	s_cselect_b32 s33, 0, s1
	s_cmp_ge_u32 s79, s33
	s_cselect_b64 s[6:7], -1, 0
	s_add_i32 s88, s33, 8
	v_readlane_b32 s1, v244, 28
	s_waitcnt lgkmcnt(1)
	v_mfma_f32_32x32x16_bf16 v[28:43], v[6:9], v[146:149], 0
	s_cmp_lt_u32 s79, s88
	v_or_b32_e32 v5, s1, v3
	s_cselect_b64 s[8:9], -1, 0
	s_sub_i32 s1, s79, s10
	s_and_b64 s[6:7], s[6:7], s[8:9]
	s_mul_i32 s1, s1, 31
	s_addk_i32 s1, 0xe8
	s_waitcnt lgkmcnt(0)
	v_mfma_f32_32x32x16_bf16 v[28:43], v[10:13], v[150:153], v[28:43]
	ds_read_b128 v[6:9], v173 offset:64
	ds_read_b128 v[10:13], v173 offset:96
	s_and_b64 vcc, s[38:39], s[6:7]
	s_and_b64 s[6:7], vcc, exec
	s_cselect_b32 s1, s1, 15
	v_med3_u32 v2, v5, 8, 56
	v_sub_u32_e32 v5, s1, v5
	v_lshlrev_b32_e32 v5, 2, v5
	s_waitcnt vmcnt(1) lgkmcnt(1)
	v_mfma_f32_32x32x16_bf16 v[44:59], v[6:9], v[154:157], v[44:59]
	ds_read_b128 v[6:9], v173 offset:4672
	ds_read_b128 v[14:17], v173 offset:4704
	s_add_i32 s1, 0, 0x16400
	v_lshlrev_b32_e32 v172, 2, v4
	v_sub_u32_e32 v2, v172, v2
	v_add_u32_e32 v2, 8, v2
	v_cndmask_b32_e32 v4, v176, v2, vcc
	v_cmp_gt_u32_e32 vcc, 16, v4
	s_waitcnt lgkmcnt(1)
	v_mfma_f32_32x32x16_bf16 v[28:43], v[6:9], v[154:157], v[28:43]
	v_add3_u32 v6, s1, v5, v0
	ds_read_b32 v5, v6 offset:128
	s_waitcnt vmcnt(0)
	v_mfma_f32_32x32x16_bf16 v[44:59], v[10:13], v[158:161], v[44:59]
	s_waitcnt lgkmcnt(1)
	v_mfma_f32_32x32x16_bf16 v[28:43], v[14:17], v[158:161], v[28:43]
	v_mov_b32_e32 v17, 0xff800000
	v_mov_b32_e32 v16, 0xff800000
	ds_read2_b32 v[16:17], v6 offset0:0 offset1:1
	ds_read2_b32 v[18:19], v6 offset0:2 offset1:3
	ds_read2_b32 v[20:21], v6 offset0:8 offset1:9
	ds_read2_b32 v[22:23], v6 offset0:10 offset1:11
	ds_read2_b32 v[24:25], v6 offset0:16 offset1:17
	ds_read2_b32 v[26:27], v6 offset0:18 offset1:19
	ds_read2_b32 v[60:61], v6 offset0:24 offset1:25
	ds_read2_b32 v[62:63], v6 offset0:26 offset1:27
	s_waitcnt lgkmcnt(0)
	v_cmp_gt_u32_e32 vcc, 16, v4
	v_add_f32_e32 v16, v44, v16
	v_add_u32_e32 v207, 1, v4
	v_cndmask_b32_e32 v16, v177, v16, vcc
	v_cmp_gt_u32_e32 vcc, 16, v207
	v_add_f32_e32 v17, v45, v17
	v_add_u32_e32 v207, 2, v4
	v_cndmask_b32_e32 v17, v177, v17, vcc
	v_cmp_gt_u32_e32 vcc, 16, v207
	v_add_f32_e32 v18, v46, v18
	v_add_u32_e32 v207, 3, v4
	v_cndmask_b32_e32 v18, v177, v18, vcc
	v_cmp_gt_u32_e32 vcc, 16, v207
	v_add_f32_e32 v19, v47, v19
	v_add_u32_e32 v207, 8, v4
	v_cndmask_b32_e32 v19, v177, v19, vcc
	v_cmp_gt_u32_e32 vcc, 16, v207
	v_add_f32_e32 v20, v48, v20
	v_add_u32_e32 v207, 9, v4
	v_cndmask_b32_e32 v20, v177, v20, vcc
	v_cmp_gt_u32_e32 vcc, 16, v207
	v_add_f32_e32 v21, v49, v21
	v_add_u32_e32 v207, 10, v4
	v_cndmask_b32_e32 v21, v177, v21, vcc
	v_cmp_gt_u32_e32 vcc, 16, v207
	v_add_f32_e32 v22, v50, v22
	v_add_u32_e32 v207, 11, v4
	v_cndmask_b32_e32 v22, v177, v22, vcc
	v_cmp_gt_u32_e32 vcc, 16, v207
	v_add_f32_e32 v23, v51, v23
	s_nop 0
	v_cndmask_b32_e32 v23, v177, v23, vcc
	v_cmp_lt_u32_e32 vcc, s40, v4
	v_add_f32_e32 v24, v52, v24
	v_add_u32_e32 v207, 17, v4
	v_cndmask_b32_e32 v24, v177, v24, vcc
	v_cmp_gt_u32_e32 vcc, 16, v207
	v_add_f32_e32 v25, v53, v25
	v_add_u32_e32 v207, 18, v4
	v_cndmask_b32_e32 v25, v177, v25, vcc
	v_cmp_gt_u32_e32 vcc, 16, v207
	v_add_f32_e32 v26, v54, v26
	v_add_u32_e32 v207, 19, v4
	v_cndmask_b32_e32 v26, v177, v26, vcc
	v_cmp_gt_u32_e32 vcc, 16, v207
	v_add_f32_e32 v27, v55, v27
	v_add_u32_e32 v207, 24, v4
	v_cndmask_b32_e32 v27, v177, v27, vcc
	v_cmp_gt_u32_e32 vcc, 16, v207
	v_add_f32_e32 v60, v56, v60
	v_add_u32_e32 v207, 25, v4
	v_cndmask_b32_e32 v60, v177, v60, vcc
	v_cmp_gt_u32_e32 vcc, 16, v207
	v_add_f32_e32 v61, v57, v61
	v_add_u32_e32 v207, 26, v4
	v_cndmask_b32_e32 v61, v177, v61, vcc
	v_cmp_gt_u32_e32 vcc, 16, v207
	v_add_f32_e32 v62, v58, v62
	v_add_u32_e32 v207, 27, v4
	v_cndmask_b32_e32 v62, v177, v62, vcc
	v_cmp_gt_u32_e32 vcc, 16, v207
	v_add_f32_e32 v63, v59, v63
	s_nop 0
	v_cndmask_b32_e32 v63, v177, v63, vcc
	ds_read_b32 v7, v6 offset:132
	ds_read_b32 v8, v6 offset:136
	ds_read_b32 v9, v6 offset:140
	ds_read_b32 v10, v6 offset:160
	ds_read_b32 v11, v6 offset:164
	ds_read_b32 v12, v6 offset:168
	ds_read_b32 v13, v6 offset:172
	ds_read_b32 v14, v6 offset:192
	ds_read_b32 v15, v6 offset:196
	ds_read_b32 v44, v6 offset:200
	ds_read_b32 v45, v6 offset:204
	ds_read_b32 v46, v6 offset:224
	ds_read_b32 v47, v6 offset:228
	ds_read_b32 v48, v6 offset:232
	ds_read_b32 v49, v6 offset:236
	s_waitcnt lgkmcnt(14)
	v_add_f32_e32 v6, v29, v7
	s_waitcnt lgkmcnt(13)
	v_add_f32_e32 v7, v30, v8
	s_waitcnt lgkmcnt(12)
	v_add_f32_e32 v8, v31, v9
	s_waitcnt lgkmcnt(11)
	v_add_f32_e32 v9, v32, v10
	s_waitcnt lgkmcnt(10)
; __device__ __forceinline__ float max3f(float a, float b, float c) { float r; asm("v_max3_f32 %0, %1, %2, %3" : "=v"(r) : "v"(a), "v"(b), "v"(c)); return r; }
; __device__ __forceinline__ float rowmax32(const f32x16& p0, const f32x16& p1) {
;     float a = max3f(p0[0], p0[1], p1[0]), b = max3f(p0[2], p0[3], p1[1]); a = max3f(a, p1[2], p1[3]);
; #pragma unroll
;     for (int r = 4; r < 16; r += 4) { a = max3f(a, p0[r], p0[r + 1]); b = max3f(b, p0[r + 2], p0[r + 3]); a = max3f(a, p1[r], p1[r + 1]); b = max3f(b, p1[r + 2], p1[r + 3]); }
;     const float m = fmaxf(a, b);
;     auto rr = __builtin_amdgcn_permlane32_swap(__float_as_uint(m), __float_as_uint(m), false, false);
;     return fmaxf(__uint_as_float(rr[0]), __uint_as_float(rr[1]));
; }
	v_add_f32_e32 v10, v33, v11
	v_add_u32_e32 v33, 33, v4
	v_cmp_gt_u32_e32 vcc, 16, v33
	v_add_u32_e32 v33, 34, v4
	v_cmp_gt_u32_e64 s[6:7], 16, v33
	v_add_u32_e32 v33, 35, v4
	v_cmp_gt_u32_e64 s[8:9], 16, v33
	v_add_u32_e32 v33, 40, v4
	v_cmp_gt_u32_e64 s[10:11], 16, v33
	v_add_u32_e32 v33, 41, v4
	v_cmp_gt_u32_e64 s[12:13], 16, v33
	v_add_u32_e32 v33, 42, v4
	v_cmp_gt_u32_e64 s[14:15], 16, v33
	v_add_u32_e32 v33, 43, v4
	v_cmp_gt_u32_e64 s[16:17], 16, v33
	v_add_u32_e32 v33, 49, v4
	v_cmp_gt_u32_e64 s[18:19], 16, v33
	v_add_u32_e32 v33, 50, v4
	v_cmp_gt_u32_e64 s[20:21], 16, v33
	v_add_u32_e32 v33, 51, v4
	v_cmp_gt_u32_e64 s[22:23], 16, v33
	v_add_u32_e32 v33, 56, v4
	v_cmp_gt_u32_e64 s[24:25], 16, v33
	v_add_u32_e32 v33, 57, v4
	v_cmp_gt_u32_e64 s[26:27], 16, v33
	v_add_u32_e32 v33, 58, v4
	v_cmp_gt_u32_e64 s[28:29], 16, v33
	v_add_u32_e32 v33, 59, v4
	v_and_b32_e32 v4, -16, v4
	v_add_f32_e32 v5, v28, v5
	v_cmp_eq_u32_e64 s[36:37], s41, v4
	v_cmp_eq_u32_e64 s[34:35], s42, v4
	v_cndmask_b32_e64 v82, v177, v7, s[6:7]
	v_cndmask_b32_e64 v80, v177, v5, s[36:37]
	v_max3_f32 v4, v16, v17, v80
	v_cndmask_b32_e64 v81, v177, v8, s[8:9]
	v_max3_f32 v4, v4, v82, v81
	v_cndmask_b32_e32 v95, v177, v6, vcc
	v_max3_f32 v5, v18, v19, v95
	s_waitcnt lgkmcnt(9)
	v_add_f32_e32 v11, v34, v12
	s_waitcnt lgkmcnt(8)
	v_add_f32_e32 v12, v35, v13
	v_max3_f32 v4, v4, v20, v21
	v_max3_f32 v5, v5, v22, v23
	v_cndmask_b32_e64 v84, v177, v9, s[10:11]
	v_cndmask_b32_e64 v89, v177, v10, s[12:13]
	v_max3_f32 v4, v4, v84, v89
	v_cndmask_b32_e64 v86, v177, v11, s[14:15]
	v_cndmask_b32_e64 v83, v177, v12, s[16:17]
	v_max3_f32 v5, v5, v86, v83
	s_waitcnt lgkmcnt(7)
	v_add_f32_e32 v13, v36, v14
	s_waitcnt lgkmcnt(6)
	v_add_f32_e32 v14, v37, v15
	s_waitcnt lgkmcnt(5)
	v_add_f32_e32 v15, v38, v44
	s_waitcnt lgkmcnt(4)
	v_add_f32_e32 v28, v39, v45
	v_max3_f32 v4, v4, v24, v25
	v_max3_f32 v5, v5, v26, v27
	v_cndmask_b32_e64 v88, v177, v13, s[34:35]
	v_cndmask_b32_e64 v91, v177, v14, s[18:19]
	v_max3_f32 v4, v4, v88, v91
	v_cndmask_b32_e64 v90, v177, v15, s[20:21]
	v_cndmask_b32_e64 v85, v177, v28, s[22:23]
	v_max3_f32 v5, v5, v90, v85
	s_waitcnt lgkmcnt(3)
	v_add_f32_e32 v29, v40, v46
	s_waitcnt lgkmcnt(2)
	v_add_f32_e32 v30, v41, v47
	s_waitcnt lgkmcnt(1)
	v_add_f32_e32 v31, v42, v48
	s_waitcnt lgkmcnt(0)
	v_add_f32_e32 v32, v43, v49
	v_cmp_gt_u32_e64 s[30:31], 16, v33
	v_max3_f32 v4, v4, v60, v61
	v_max3_f32 v5, v5, v62, v63
	v_cndmask_b32_e64 v92, v177, v29, s[24:25]
	v_cndmask_b32_e64 v93, v177, v30, s[26:27]
	v_max3_f32 v4, v4, v92, v93
	v_cndmask_b32_e64 v94, v177, v31, s[28:29]
	v_cndmask_b32_e64 v87, v177, v32, s[30:31]
	v_max3_f32 v5, v5, v94, v87
	v_max_f32_e32 v4, v4, v5
	v_mov_b32_e32 v5, v4
	s_nop 1
	v_permlane32_swap_b32_e32 v4, v5
	s_and_b64 vcc, exec, s[38:39]
	s_barrier
	s_cbranch_vccz .LBB0_868
	v_max_f32_e32 v180, v4, v5
	v_and_b32_e32 v4, -16, v2
	s_movk_i32 s1, 0xffef
	v_cmp_eq_u32_e64 s[8:9], s41, v4
	v_add_u32_e32 v5, 1, v2
	v_cmp_lt_u32_e64 s[40:41], s1, v2
	s_movk_i32 s1, 0xffd0
	v_cmp_gt_u32_e64 s[10:11], 16, v5
	v_add_u32_e32 v5, 33, v2
	v_cmp_eq_u32_e64 s[42:43], s1, v4
	v_add_u32_e32 v4, 17, v2
	v_cmp_gt_u32_e64 s[12:13], 16, v5
	v_add_u32_e32 v5, 2, v2
	v_cmp_gt_u32_e64 s[44:45], 16, v4
	v_add_u32_e32 v4, 49, v2
	v_cmp_gt_u32_e64 s[14:15], 16, v5
	v_add_u32_e32 v5, 34, v2
	v_cmp_gt_u32_e64 s[46:47], 16, v4
	v_add_u32_e32 v4, 18, v2
	v_cmp_gt_u32_e64 s[16:17], 16, v5
	v_add_u32_e32 v5, 3, v2
	v_cmp_gt_u32_e64 s[48:49], 16, v4
	v_add_u32_e32 v4, 50, v2
	v_cmp_gt_u32_e64 s[18:19], 16, v5
	v_add_u32_e32 v5, 35, v2
	v_cmp_gt_u32_e64 s[50:51], 16, v4
	v_add_u32_e32 v4, 19, v2
	v_cmp_gt_u32_e64 s[20:21], 16, v5
	v_add_u32_e32 v5, 8, v2
	v_cmp_gt_u32_e64 s[52:53], 16, v4
	v_add_u32_e32 v4, 51, v2
	v_cmp_gt_u32_e64 s[22:23], 16, v5
	v_add_u32_e32 v5, 40, v2
	v_cmp_gt_u32_e64 s[54:55], 16, v4
	v_add_u32_e32 v4, 24, v2
	v_cmp_gt_u32_e64 s[24:25], 16, v5
	v_add_u32_e32 v5, 9, v2
	v_cmp_gt_u32_e64 s[56:57], 16, v4
	v_add_u32_e32 v4, 56, v2
	v_cmp_gt_u32_e64 s[26:27], 16, v5
	v_add_u32_e32 v5, 41, v2
	v_cmp_gt_u32_e64 s[58:59], 16, v4
	v_add_u32_e32 v4, 25, v2
	v_cmp_gt_u32_e64 s[28:29], 16, v5
	v_add_u32_e32 v5, 10, v2
	v_cmp_gt_u32_e64 s[60:61], 16, v4
	v_add_u32_e32 v4, 57, v2
	v_cmp_gt_u32_e64 s[30:31], 16, v5
	v_add_u32_e32 v5, 42, v2
	v_cmp_gt_u32_e64 s[62:63], 16, v4
	v_add_u32_e32 v4, 26, v2
	v_cmp_gt_u32_e64 s[34:35], 16, v5
	v_add_u32_e32 v5, 11, v2
	v_cmp_gt_u32_e64 s[64:65], 16, v4
	v_add_u32_e32 v4, 58, v2
	v_cmp_gt_u32_e64 s[6:7], 16, v2
	v_cmp_gt_u32_e64 s[36:37], 16, v5
	v_add_u32_e32 v5, 43, v2
	v_cmp_gt_u32_e64 s[66:67], 16, v4
	v_add_u32_e32 v4, 27, v2
	v_add_u32_e32 v2, 59, v2
	s_mul_i32 s1, s79, 0x7c
	v_cmp_gt_u32_e64 s[70:71], 16, v2
	v_add_u32_e32 v0, s1, v0
	v_lshlrev_b32_e32 v2, 2, v3
	v_sub_u32_e32 v0, v0, v2
	s_mulk_i32 s0, 0x1f0
	v_subrev_u32_e32 v0, s0, v0
	v_readlane_b32 s0, v244, 29
	v_mov_b32_e32 v14, v1
	v_mov_b32_e32 v15, v1
	v_cmp_gt_u32_e64 s[38:39], 16, v5
	v_cmp_gt_u32_e64 s[68:69], 16, v4
	v_add_u32_e32 v179, s0, v0
	v_mov_b32_e32 v0, v1
	v_mov_b32_e32 v2, v1
	v_mov_b32_e32 v3, v1
	v_mov_b32_e32 v4, v1
	v_mov_b32_e32 v5, v1
	v_mov_b32_e32 v6, v1
	v_mov_b32_e32 v7, v1
	v_mov_b32_e32 v8, v1
	v_mov_b32_e32 v9, v1
	v_mov_b32_e32 v10, v1
	v_mov_b32_e32 v11, v1
	v_mov_b32_e32 v12, v1
	v_mov_b32_e32 v13, v1
	v_mov_b32_e32 v178, 0
	v_mov_b64_e32 v[58:59], v[14:15]
	v_mov_b64_e32 v[42:43], v[14:15]
	s_sub_i32 s83, s79, s33
	s_mov_b32 s1, 4
	v_mov_b64_e32 v[56:57], v[12:13]
	v_mov_b64_e32 v[54:55], v[10:11]
	v_mov_b64_e32 v[52:53], v[8:9]
	v_mov_b64_e32 v[50:51], v[6:7]
	v_mov_b64_e32 v[48:49], v[4:5]
	v_mov_b64_e32 v[46:47], v[2:3]
	v_mov_b64_e32 v[44:45], v[0:1]
	v_mov_b64_e32 v[40:41], v[12:13]
	v_mov_b64_e32 v[38:39], v[10:11]
	v_mov_b64_e32 v[36:37], v[8:9]
	v_mov_b64_e32 v[34:35], v[6:7]
	v_mov_b64_e32 v[32:33], v[4:5]
	v_mov_b64_e32 v[30:31], v[2:3]
	v_mov_b64_e32 v[28:29], v[0:1]
	v_mov_b32_e32 v2, 0
	v_mov_b32_e32 v112, 0
	v_mov_b32_e32 v113, v178
	v_mov_b32_e32 v114, v178
	v_mov_b32_e32 v115, v178
	v_mov_b32_e32 v116, v178
	v_mov_b32_e32 v117, v178
	v_mov_b32_e32 v118, v178
	v_mov_b32_e32 v119, v178
	v_mov_b32_e32 v120, v178
	v_mov_b32_e32 v121, v178
	v_mov_b32_e32 v122, v178
	v_mov_b32_e32 v123, v178
	v_mov_b32_e32 v124, v178
	v_mov_b32_e32 v125, v178
	v_mov_b32_e32 v126, v178
	v_mov_b32_e32 v127, v178
	s_branch .LBB0_768

; __device__ __forceinline__ float max3f(float a, float b, float c) { float r; asm("v_max3_f32 %0, %1, %2, %3" : "=v"(r) : "v"(a), "v"(b), "v"(c)); return r; }
; __device__ __forceinline__ float rowmax32(const f32x16& p0, const f32x16& p1) {
;     float a = max3f(p0[0], p0[1], p1[0]), b = max3f(p0[2], p0[3], p1[1]); a = max3f(a, p1[2], p1[3]);
; #pragma unroll
;     for (int r = 4; r < 16; r += 4) { a = max3f(a, p0[r], p0[r + 1]); b = max3f(b, p0[r + 2], p0[r + 3]); a = max3f(a, p1[r], p1[r + 1]); b = max3f(b, p1[r + 2], p1[r + 3]); }
;     const float m = fmaxf(a, b);
;     auto rr = __builtin_amdgcn_permlane32_swap(__float_as_uint(m), __float_as_uint(m), false, false);
;     return fmaxf(__uint_as_float(rr[0]), __uint_as_float(rr[1]));
; }
.LBB0_779:
.LBB0_780:
.LBB0_781:
.LBB0_782:
	s_add_i32 s87, s1, -4
	s_add_i32 s0, s74, -3
	s_cmp_ge_i32 s0, s33
	s_cselect_b64 s[94:95], -1, 0
	s_cmp_lt_i32 s0, s88
	s_cselect_b64 s[96:97], -1, 0
	s_and_b64 s[94:95], s[94:95], s[96:97]
	s_add_i32 s0, s1, -3
	s_cmp_lt_i32 s87, s81
	s_cselect_b64 s[96:97], -1, 0
	s_and_b64 vcc, s[94:95], s[96:97]
	s_andn2_b64 vcc, exec, vcc
	s_cbranch_vccnz .LBB0_817
	s_and_b32 s90, s0, 3
	s_mulk_i32 s90, 0x3400
	v_add_u32_e32 v0, s90, v173
	ds_read_b128 v[64:67], v0 offset:4608
	ds_read_b128 v[68:71], v0
	ds_read_b128 v[72:75], v0 offset:32
	ds_read_b128 v[220:223], v0 offset:4640
	ds_read_b128 v[224:227], v0 offset:64
	ds_read_b128 v[228:231], v0 offset:4672
	ds_read_b128 v[232:235], v0 offset:96
	ds_read_b128 v[236:239], v0 offset:4704
	s_waitcnt lgkmcnt(7)
	v_mfma_f32_32x32x16_bf16 v[96:111], v[64:67], v[146:149], v[112:127]
	s_waitcnt lgkmcnt(6)
	v_mfma_f32_32x32x16_bf16 v[130:145], v[68:71], v[146:149], v[112:127]
	s_waitcnt lgkmcnt(5)
	v_mfma_f32_32x32x16_bf16 v[130:145], v[72:75], v[150:153], v[130:145]
	s_waitcnt lgkmcnt(4)
	v_mfma_f32_32x32x16_bf16 v[96:111], v[220:223], v[150:153], v[96:111]
	s_waitcnt lgkmcnt(3)
	v_mfma_f32_32x32x16_bf16 v[130:145], v[224:227], v[154:157], v[130:145]
	s_waitcnt lgkmcnt(2)
	v_mfma_f32_32x32x16_bf16 v[96:111], v[228:231], v[154:157], v[96:111]
	s_waitcnt lgkmcnt(1)
	v_mfma_f32_32x32x16_bf16 v[130:145], v[232:235], v[158:161], v[130:145]
	s_waitcnt lgkmcnt(0)
	v_mfma_f32_32x32x16_bf16 v[96:111], v[236:239], v[158:161], v[96:111]
	ds_read_b32 v0, v179 offset:128
	ds_read2_b32 v[64:65], v179 offset0:0 offset1:1
	ds_read2_b32 v[66:67], v179 offset0:2 offset1:3
	ds_read2_b32 v[68:69], v179 offset0:8 offset1:9
	ds_read2_b32 v[70:71], v179 offset0:10 offset1:11
	ds_read2_b32 v[72:73], v179 offset0:16 offset1:17
	ds_read2_b32 v[74:75], v179 offset0:18 offset1:19
	ds_read2_b32 v[76:77], v179 offset0:24 offset1:25
	ds_read2_b32 v[78:79], v179 offset0:26 offset1:27
	s_waitcnt lgkmcnt(0)
	v_add_f32_e32 v64, v130, v64
	v_cndmask_b32_e64 v64, v177, v64, s[6:7]
	v_add_f32_e32 v65, v131, v65
	v_cndmask_b32_e64 v65, v177, v65, s[10:11]
	v_add_f32_e32 v66, v132, v66
	v_cndmask_b32_e64 v66, v177, v66, s[14:15]
	v_add_f32_e32 v67, v133, v67
	v_cndmask_b32_e64 v67, v177, v67, s[18:19]
	v_add_f32_e32 v68, v134, v68
	v_cndmask_b32_e64 v68, v177, v68, s[22:23]
	v_add_f32_e32 v69, v135, v69
	v_cndmask_b32_e64 v69, v177, v69, s[26:27]
	v_add_f32_e32 v70, v136, v70
	v_cndmask_b32_e64 v70, v177, v70, s[30:31]
	v_add_f32_e32 v71, v137, v71
	v_cndmask_b32_e64 v71, v177, v71, s[36:37]
	v_add_f32_e32 v72, v138, v72
	v_cndmask_b32_e64 v72, v177, v72, s[40:41]
	v_add_f32_e32 v73, v139, v73
	v_cndmask_b32_e64 v73, v177, v73, s[44:45]
	v_add_f32_e32 v74, v140, v74
	v_cndmask_b32_e64 v74, v177, v74, s[48:49]
	v_add_f32_e32 v75, v141, v75
	v_cndmask_b32_e64 v75, v177, v75, s[52:53]
	v_add_f32_e32 v76, v142, v76
	v_cndmask_b32_e64 v76, v177, v76, s[56:57]
	v_add_f32_e32 v77, v143, v77
	v_cndmask_b32_e64 v77, v177, v77, s[60:61]
	v_add_f32_e32 v78, v144, v78
	v_cndmask_b32_e64 v78, v177, v78, s[64:65]
	v_add_f32_e32 v79, v145, v79
	v_cndmask_b32_e64 v79, v177, v79, s[68:69]
	ds_read_b32 v3, v179 offset:132
	ds_read_b32 v129, v179 offset:136
	ds_read_b32 v130, v179 offset:140
	ds_read_b32 v131, v179 offset:160
	ds_read_b32 v132, v179 offset:164
	ds_read_b32 v133, v179 offset:168
	ds_read_b32 v134, v179 offset:172
	ds_read_b32 v135, v179 offset:192
	ds_read_b32 v136, v179 offset:196
	ds_read_b32 v137, v179 offset:200
	ds_read_b32 v138, v179 offset:204
	ds_read_b32 v139, v179 offset:224
	ds_read_b32 v140, v179 offset:228
	ds_read_b32 v142, v179 offset:232
	ds_read_b32 v141, v179 offset:236
	s_waitcnt lgkmcnt(14)
	v_add_f32_e32 v0, v96, v0
	v_cndmask_b32_e64 v96, v177, v0, s[8:9]
	v_add_f32_e32 v0, v97, v3
	v_cndmask_b32_e64 v97, v177, v0, s[12:13]
	s_waitcnt lgkmcnt(13)
	v_add_f32_e32 v0, v98, v129
	v_cndmask_b32_e64 v98, v177, v0, s[16:17]
	s_waitcnt lgkmcnt(12)
	v_add_f32_e32 v0, v99, v130
	v_cndmask_b32_e64 v99, v177, v0, s[20:21]
	s_waitcnt lgkmcnt(11)
	v_add_f32_e32 v0, v100, v131
	v_cndmask_b32_e64 v100, v177, v0, s[24:25]
	s_waitcnt lgkmcnt(10)
	v_add_f32_e32 v0, v101, v132
	v_cndmask_b32_e64 v101, v177, v0, s[28:29]
	s_waitcnt lgkmcnt(9)
	v_add_f32_e32 v0, v102, v133
	v_cndmask_b32_e64 v102, v177, v0, s[34:35]
	s_waitcnt lgkmcnt(8)
	v_add_f32_e32 v0, v103, v134
	v_cndmask_b32_e64 v103, v177, v0, s[38:39]
	s_waitcnt lgkmcnt(7)
	v_add_f32_e32 v0, v104, v135
	v_cndmask_b32_e64 v104, v177, v0, s[42:43]
	s_waitcnt lgkmcnt(6)
	v_add_f32_e32 v0, v105, v136
	v_cndmask_b32_e64 v105, v177, v0, s[46:47]
	s_waitcnt lgkmcnt(5)
	v_add_f32_e32 v0, v106, v137
	v_cndmask_b32_e64 v106, v177, v0, s[50:51]
	s_waitcnt lgkmcnt(4)
	v_add_f32_e32 v0, v107, v138
	v_cndmask_b32_e64 v107, v177, v0, s[54:55]
	s_waitcnt lgkmcnt(3)
	v_add_f32_e32 v0, v108, v139
	v_cndmask_b32_e64 v108, v177, v0, s[58:59]
	s_waitcnt lgkmcnt(2)
	v_add_f32_e32 v0, v109, v140
	v_cndmask_b32_e64 v109, v177, v0, s[62:63]
	s_waitcnt lgkmcnt(1)
	v_add_f32_e32 v0, v110, v142
	v_cndmask_b32_e64 v110, v177, v0, s[66:67]
	s_waitcnt lgkmcnt(0)
	v_add_f32_e32 v0, v111, v141
	v_cndmask_b32_e64 v111, v177, v0, s[70:71]
	v_max3_f32 v0, v64, v65, v96
	v_max3_f32 v3, v66, v67, v97
	v_max3_f32 v0, v0, v98, v99
	v_max3_f32 v3, v3, v70, v71
	v_max3_f32 v0, v0, v68, v69
	v_max3_f32 v3, v3, v102, v103
	v_max3_f32 v0, v0, v100, v101
	v_max3_f32 v3, v3, v74, v75
	v_max3_f32 v0, v0, v72, v73
	v_max3_f32 v3, v3, v106, v107
	v_max3_f32 v0, v0, v104, v105
	v_max3_f32 v3, v3, v78, v79
	v_max3_f32 v0, v0, v76, v77
	v_max3_f32 v3, v3, v110, v111
	v_max3_f32 v0, v0, v108, v109
	v_max_f32_e32 v0, v0, v3
	v_mov_b32_e32 v3, v0
	s_nop 1
	v_permlane32_swap_b32_e32 v0, v3
	v_max_f32_e32 v3, v0, v3
	s_and_b64 vcc, exec, s[72:73]
	s_cbranch_vccz .LBB0_818

; __device__ __forceinline__ float max3f(float a, float b, float c) { float r; asm("v_max3_f32 %0, %1, %2, %3" : "=v"(r) : "v"(a), "v"(b), "v"(c)); return r; }
; __device__ __forceinline__ float rowmax32(const f32x16& p0, const f32x16& p1) {
;     float a = max3f(p0[0], p0[1], p1[0]), b = max3f(p0[2], p0[3], p1[1]); a = max3f(a, p1[2], p1[3]);
; #pragma unroll
;     for (int r = 4; r < 16; r += 4) { a = max3f(a, p0[r], p0[r + 1]); b = max3f(b, p0[r + 2], p0[r + 3]); a = max3f(a, p1[r], p1[r + 1]); b = max3f(b, p1[r + 2], p1[r + 3]); }
;     const float m = fmaxf(a, b);
;     auto rr = __builtin_amdgcn_permlane32_swap(__float_as_uint(m), __float_as_uint(m), false, false);
;     return fmaxf(__uint_as_float(rr[0]), __uint_as_float(rr[1]));
; }
.LBB0_829:
	s_add_i32 s74, s74, -2
	s_cmp_ge_i32 s74, s33
	s_cselect_b64 s[90:91], -1, 0
	s_cmp_lt_i32 s74, s88
	s_cselect_b64 s[94:95], -1, 0
	s_and_b64 s[90:91], s[90:91], s[94:95]
	s_cmp_le_i32 s85, s81
	s_cselect_b64 s[94:95], -1, 0
	s_and_b64 s[90:91], s[90:91], s[94:95]
	s_andn2_b64 vcc, exec, s[90:91]
	s_cbranch_vccnz .LBB0_863
	s_mulk_i32 s77, 0x3400
	v_add_u32_e32 v0, s77, v173
	ds_read_b128 v[4:7], v0 offset:4608
	ds_read_b128 v[8:11], v0
	ds_read_b128 v[12:15], v0 offset:32
	ds_read_b128 v[220:223], v0 offset:4640
	ds_read_b128 v[224:227], v0 offset:64
	ds_read_b128 v[228:231], v0 offset:4672
	ds_read_b128 v[232:235], v0 offset:96
	ds_read_b128 v[236:239], v0 offset:4704
	v_mov_b32_e32 v17, 0xff800000
	v_mov_b32_e32 v16, 0xff800000
	s_waitcnt lgkmcnt(6)
	v_mfma_f32_32x32x16_bf16 v[80:95], v[8:11], v[146:149], v[112:127]
	v_mfma_f32_32x32x16_bf16 v[130:145], v[4:7], v[146:149], v[112:127]
	s_waitcnt lgkmcnt(5)
	v_mfma_f32_32x32x16_bf16 v[80:95], v[12:15], v[150:153], v[80:95]
	s_waitcnt lgkmcnt(4)
	v_mfma_f32_32x32x16_bf16 v[130:145], v[220:223], v[150:153], v[130:145]
	s_waitcnt lgkmcnt(3)
	v_mfma_f32_32x32x16_bf16 v[80:95], v[224:227], v[154:157], v[80:95]
	s_waitcnt lgkmcnt(2)
	v_mfma_f32_32x32x16_bf16 v[130:145], v[228:231], v[154:157], v[130:145]
	s_waitcnt lgkmcnt(1)
	v_mfma_f32_32x32x16_bf16 v[80:95], v[232:235], v[158:161], v[80:95]
	s_waitcnt lgkmcnt(0)
	v_mfma_f32_32x32x16_bf16 v[130:145], v[236:239], v[158:161], v[130:145]
	ds_read_b32 v0, v179 offset:252
	ds_read2_b32 v[16:17], v179 offset0:31 offset1:32
	ds_read2_b32 v[18:19], v179 offset0:33 offset1:34
	ds_read2_b32 v[20:21], v179 offset0:39 offset1:40
	ds_read2_b32 v[22:23], v179 offset0:41 offset1:42
	ds_read2_b32 v[24:25], v179 offset0:47 offset1:48
	ds_read2_b32 v[26:27], v179 offset0:49 offset1:50
	ds_read2_b32 v[60:61], v179 offset0:55 offset1:56
	ds_read2_b32 v[62:63], v179 offset0:57 offset1:58
	s_waitcnt lgkmcnt(0)
	v_add_f32_e32 v16, v80, v16
	v_cndmask_b32_e64 v16, v177, v16, s[6:7]
	v_add_f32_e32 v17, v81, v17
	v_cndmask_b32_e64 v17, v177, v17, s[10:11]
	v_add_f32_e32 v18, v82, v18
	v_cndmask_b32_e64 v18, v177, v18, s[14:15]
	v_add_f32_e32 v19, v83, v19
	v_cndmask_b32_e64 v19, v177, v19, s[18:19]
	v_add_f32_e32 v20, v84, v20
	v_cndmask_b32_e64 v20, v177, v20, s[22:23]
	v_add_f32_e32 v21, v85, v21
	v_cndmask_b32_e64 v21, v177, v21, s[26:27]
	v_add_f32_e32 v22, v86, v22
	v_cndmask_b32_e64 v22, v177, v22, s[30:31]
	v_add_f32_e32 v23, v87, v23
	v_cndmask_b32_e64 v23, v177, v23, s[36:37]
	v_add_f32_e32 v24, v88, v24
	v_cndmask_b32_e64 v24, v177, v24, s[40:41]
	v_add_f32_e32 v25, v89, v25
	v_cndmask_b32_e64 v25, v177, v25, s[44:45]
	v_add_f32_e32 v26, v90, v26
	v_cndmask_b32_e64 v26, v177, v26, s[48:49]
	v_add_f32_e32 v27, v91, v27
	v_cndmask_b32_e64 v27, v177, v27, s[52:53]
	v_add_f32_e32 v60, v92, v60
	v_cndmask_b32_e64 v60, v177, v60, s[56:57]
	v_add_f32_e32 v61, v93, v61
	v_cndmask_b32_e64 v61, v177, v61, s[60:61]
	v_add_f32_e32 v62, v94, v62
	v_cndmask_b32_e64 v62, v177, v62, s[64:65]
	v_add_f32_e32 v63, v95, v63
	v_cndmask_b32_e64 v63, v177, v63, s[68:69]
	ds_read_b32 v4, v179 offset:256
	ds_read_b32 v5, v179 offset:260
	ds_read_b32 v6, v179 offset:264
	ds_read_b32 v7, v179 offset:284
	ds_read_b32 v8, v179 offset:288
	ds_read_b32 v9, v179 offset:292
	ds_read_b32 v10, v179 offset:296
	ds_read_b32 v11, v179 offset:316
	ds_read_b32 v12, v179 offset:320
	ds_read_b32 v13, v179 offset:324
	ds_read_b32 v14, v179 offset:328
	ds_read_b32 v15, v179 offset:348
	ds_read_b32 v80, v179 offset:352
	ds_read_b32 v82, v179 offset:356
	ds_read_b32 v81, v179 offset:360
	s_waitcnt lgkmcnt(14)
	v_add_f32_e32 v0, v130, v0
	v_add_f32_e32 v4, v131, v4
	s_waitcnt lgkmcnt(13)
	v_add_f32_e32 v5, v132, v5
	s_waitcnt lgkmcnt(12)
	v_add_f32_e32 v6, v133, v6
	s_waitcnt lgkmcnt(2)
	v_add_f32_e32 v87, v143, v80
	v_cndmask_b32_e64 v80, v177, v0, s[8:9]
	v_max3_f32 v0, v16, v17, v80
	s_waitcnt lgkmcnt(1)
	v_add_f32_e32 v94, v144, v82
	s_waitcnt lgkmcnt(0)
	v_add_f32_e32 v128, v145, v81
	v_cndmask_b32_e64 v82, v177, v5, s[16:17]
	v_cndmask_b32_e64 v81, v177, v6, s[20:21]
	v_max3_f32 v0, v0, v82, v81
	v_cndmask_b32_e64 v95, v177, v4, s[12:13]
	v_max3_f32 v4, v18, v19, v95
	v_add_f32_e32 v7, v134, v7
	v_add_f32_e32 v8, v135, v8
	v_add_f32_e32 v9, v136, v9
	v_add_f32_e32 v10, v137, v10
	v_max3_f32 v0, v0, v20, v21
	v_max3_f32 v4, v4, v22, v23
	v_cndmask_b32_e64 v84, v177, v7, s[24:25]
	v_cndmask_b32_e64 v89, v177, v8, s[28:29]
	v_max3_f32 v0, v0, v84, v89
	v_cndmask_b32_e64 v86, v177, v9, s[34:35]
	v_cndmask_b32_e64 v83, v177, v10, s[38:39]
	v_max3_f32 v4, v4, v86, v83
	v_add_f32_e32 v11, v138, v11
	v_add_f32_e32 v12, v139, v12
	v_add_f32_e32 v13, v140, v13
	v_add_f32_e32 v14, v141, v14
	v_max3_f32 v0, v0, v24, v25
	v_max3_f32 v4, v4, v26, v27
	v_cndmask_b32_e64 v88, v177, v11, s[42:43]
	v_cndmask_b32_e64 v91, v177, v12, s[46:47]
	v_max3_f32 v0, v0, v88, v91
	v_cndmask_b32_e64 v90, v177, v13, s[50:51]
	v_cndmask_b32_e64 v85, v177, v14, s[54:55]
	v_max3_f32 v4, v4, v90, v85
	v_add_f32_e32 v15, v142, v15
	v_max3_f32 v0, v0, v60, v61
	v_max3_f32 v4, v4, v62, v63
	v_cndmask_b32_e64 v92, v177, v15, s[58:59]
	v_cndmask_b32_e64 v93, v177, v87, s[62:63]
	v_max3_f32 v0, v0, v92, v93
	v_cndmask_b32_e64 v94, v177, v94, s[66:67]
	v_cndmask_b32_e64 v87, v177, v128, s[70:71]
	v_max3_f32 v4, v4, v94, v87
	v_max_f32_e32 v0, v0, v4
	v_mov_b32_e32 v4, v0
	s_nop 1
	v_permlane32_swap_b32_e32 v0, v4
	v_max_f32_e32 v180, v0, v4
